# v135 plus warm-up touches of W_dn (before the up-projection's last tile round) and of the next layer's W_in (when layer 0's down-projection enters its epilogue)
# baseline (speedup 1.0000x reference)
.LBB0_41:
	s_add_u32 s54, s52, 0xffe00080
	s_addc_u32 s55, s53, -1
	s_add_i32 s64, 0, 0x10000
	s_cmpk_eq_i32 s63, 0x7c
	s_cselect_b32 s57, s4, s55
	s_cselect_b32 s56, s5, s54
	s_cselect_b32 s55, s37, s62
	s_cselect_b32 s54, s43, s61
	s_add_i32 s66, 0, 0x14000
	v_add_u32_e32 v156, s64, v163
	v_add_u32_e32 v160, s66, v163
	ds_read_b128 v[134:137], v156
	ds_read_b128 v[138:141], v156 offset:1024
	ds_read_b128 v[152:155], v156 offset:2048
	ds_read_b128 v[156:159], v156 offset:3072
	ds_read_b128 v[166:169], v160
	ds_read_b128 v[170:173], v160 offset:1024
	ds_read_b128 v[174:177], v160 offset:2048
	ds_read_b128 v[178:181], v160 offset:3072
	v_lshl_add_u64 v[160:161], s[52:53], 0, v[150:151]
	s_add_i32 m0, s21, 0xc000
	ds_read_b128 v[182:185], v165
	ds_read_b128 v[186:189], v165 offset:1024
	ds_read_b128 v[198:201], v165 offset:2048
	ds_read_b128 v[202:205], v165 offset:3072
	ds_read_b128 v[206:209], v165 offset:4096
	ds_read_b128 v[210:213], v165 offset:5120
	ds_read_b128 v[214:217], v165 offset:6144
	ds_read_b128 v[236:239], v165 offset:7168
	global_load_lds_dwordx4 v[160:161], off
	v_lshl_add_u64 v[160:161], s[52:53], 0, v[148:149]
	s_add_i32 m0, s21, 0xe000
	s_nop 0
	global_load_lds_dwordx4 v[160:161], off
	s_waitcnt vmcnt(8)
	s_waitcnt lgkmcnt(0)
	s_barrier
	s_setprio 1
	s_waitcnt lgkmcnt(0)
	v_mfma_f32_16x16x32_bf16 v[130:133], v[134:137], v[182:185], v[130:133]
	v_mfma_f32_16x16x32_bf16 v[126:129], v[152:155], v[182:185], v[126:129]
	v_mfma_f32_16x16x32_bf16 v[114:117], v[134:137], v[198:201], v[114:117]
	v_mfma_f32_16x16x32_bf16 v[110:113], v[152:155], v[198:201], v[110:113]
	v_mfma_f32_16x16x32_bf16 v[98:101], v[134:137], v[206:209], v[98:101]
	v_mfma_f32_16x16x32_bf16 v[94:97], v[152:155], v[206:209], v[94:97]
	v_mfma_f32_16x16x32_bf16 v[82:85], v[134:137], v[214:217], v[82:85]
	v_mfma_f32_16x16x32_bf16 v[78:81], v[152:155], v[214:217], v[78:81]
	v_mfma_f32_16x16x32_bf16 v[130:133], v[138:141], v[186:189], v[130:133]
	v_mfma_f32_16x16x32_bf16 v[126:129], v[156:159], v[186:189], v[126:129]
	v_mfma_f32_16x16x32_bf16 v[114:117], v[138:141], v[202:205], v[114:117]
	v_mfma_f32_16x16x32_bf16 v[110:113], v[156:159], v[202:205], v[110:113]
	v_mfma_f32_16x16x32_bf16 v[98:101], v[138:141], v[210:213], v[98:101]
	v_mfma_f32_16x16x32_bf16 v[94:97], v[156:159], v[210:213], v[94:97]
	v_mfma_f32_16x16x32_bf16 v[82:85], v[138:141], v[236:239], v[82:85]
	v_mfma_f32_16x16x32_bf16 v[78:81], v[156:159], v[236:239], v[78:81]
	s_setprio 0
	s_setprio 1
	v_mfma_f32_16x16x32_bf16 v[122:125], v[166:169], v[182:185], v[122:125]
	v_mfma_f32_16x16x32_bf16 v[118:121], v[174:177], v[182:185], v[118:121]
	v_mfma_f32_16x16x32_bf16 v[106:109], v[166:169], v[198:201], v[106:109]
	v_mfma_f32_16x16x32_bf16 v[102:105], v[174:177], v[198:201], v[102:105]
	v_mfma_f32_16x16x32_bf16 v[90:93], v[166:169], v[206:209], v[90:93]
	v_mfma_f32_16x16x32_bf16 v[86:89], v[174:177], v[206:209], v[86:89]
	v_mfma_f32_16x16x32_bf16 v[74:77], v[166:169], v[214:217], v[74:77]
	v_mfma_f32_16x16x32_bf16 v[70:73], v[174:177], v[214:217], v[70:73]
	v_mfma_f32_16x16x32_bf16 v[122:125], v[170:173], v[186:189], v[122:125]
	v_mfma_f32_16x16x32_bf16 v[118:121], v[178:181], v[186:189], v[118:121]
	v_mfma_f32_16x16x32_bf16 v[106:109], v[170:173], v[202:205], v[106:109]
	v_mfma_f32_16x16x32_bf16 v[102:105], v[178:181], v[202:205], v[102:105]
	v_mfma_f32_16x16x32_bf16 v[90:93], v[170:173], v[210:213], v[90:93]
	v_mfma_f32_16x16x32_bf16 v[86:89], v[178:181], v[210:213], v[86:89]
	v_mfma_f32_16x16x32_bf16 v[74:77], v[170:173], v[236:239], v[74:77]
	v_mfma_f32_16x16x32_bf16 v[70:73], v[178:181], v[236:239], v[70:73]
	s_setprio 0
	s_barrier
	s_add_i32 s64, s64, s15
	v_lshl_add_u64 v[160:161], s[54:55], 0, v[190:191]
	s_mov_b32 m0, s64
	ds_read_b128 v[182:185], v165 offset:16384
	ds_read_b128 v[186:189], v165 offset:17408
	ds_read_b128 v[198:201], v165 offset:18432
	ds_read_b128 v[202:205], v165 offset:19456
	ds_read_b128 v[206:209], v165 offset:20480
	ds_read_b128 v[210:213], v165 offset:21504
	ds_read_b128 v[214:217], v165 offset:22528
	ds_read_b128 v[236:239], v165 offset:23552
	global_load_lds_dwordx4 v[160:161], off
	s_add_i32 m0, s64, 0x2000
	s_add_u32 s64, s54, 0x200000
	v_lshl_add_u64 v[218:219], s[54:55], 0, v[146:147]
	s_addc_u32 s65, s55, 0
	s_add_i32 s66, s66, s15
	global_load_lds_dwordx4 v[218:219], off
	v_lshl_add_u64 v[240:241], s[64:65], 0, v[190:191]
	s_mov_b32 m0, s66
	v_lshl_add_u64 v[242:243], s[56:57], 0, v[144:145]
	global_load_lds_dwordx4 v[240:241], off
	v_lshl_add_u64 v[240:241], s[64:65], 0, v[146:147]
	s_add_i32 m0, s66, 0x2000
	s_nop 0
	global_load_lds_dwordx4 v[240:241], off
	v_lshl_add_u64 v[240:241], s[56:57], 0, v[142:143]
	s_mov_b32 m0, s21
	s_nop 0
	global_load_lds_dwordx4 v[240:241], off
	s_mov_b32 m0, s23
	s_nop 0
	global_load_lds_dwordx4 v[242:243], off
	s_waitcnt vmcnt(8)
	s_waitcnt lgkmcnt(0)
	s_barrier
	s_setprio 1
	s_waitcnt lgkmcnt(0)
	v_mfma_f32_16x16x32_bf16 v[66:69], v[134:137], v[182:185], v[66:69]
	v_mfma_f32_16x16x32_bf16 v[62:65], v[152:155], v[182:185], v[62:65]
	v_mfma_f32_16x16x32_bf16 v[50:53], v[134:137], v[198:201], v[50:53]
	v_mfma_f32_16x16x32_bf16 v[46:49], v[152:155], v[198:201], v[46:49]
	v_mfma_f32_16x16x32_bf16 v[34:37], v[134:137], v[206:209], v[34:37]
	v_mfma_f32_16x16x32_bf16 v[30:33], v[152:155], v[206:209], v[30:33]
	v_mfma_f32_16x16x32_bf16 v[18:21], v[134:137], v[214:217], v[18:21]
	v_mfma_f32_16x16x32_bf16 v[14:17], v[152:155], v[214:217], v[14:17]
	v_mfma_f32_16x16x32_bf16 v[66:69], v[138:141], v[186:189], v[66:69]
	v_mfma_f32_16x16x32_bf16 v[62:65], v[156:159], v[186:189], v[62:65]
	v_mfma_f32_16x16x32_bf16 v[50:53], v[138:141], v[202:205], v[50:53]
	v_mfma_f32_16x16x32_bf16 v[46:49], v[156:159], v[202:205], v[46:49]
	v_mfma_f32_16x16x32_bf16 v[34:37], v[138:141], v[210:213], v[34:37]
	v_mfma_f32_16x16x32_bf16 v[30:33], v[156:159], v[210:213], v[30:33]
	v_mfma_f32_16x16x32_bf16 v[18:21], v[138:141], v[236:239], v[18:21]
	v_mfma_f32_16x16x32_bf16 v[14:17], v[156:159], v[236:239], v[14:17]
	s_setprio 0
	s_setprio 1
	v_mfma_f32_16x16x32_bf16 v[58:61], v[166:169], v[182:185], v[58:61]
	v_mfma_f32_16x16x32_bf16 v[54:57], v[174:177], v[182:185], v[54:57]
	v_mfma_f32_16x16x32_bf16 v[42:45], v[166:169], v[198:201], v[42:45]
	v_mfma_f32_16x16x32_bf16 v[38:41], v[174:177], v[198:201], v[38:41]
	v_mfma_f32_16x16x32_bf16 v[26:29], v[166:169], v[206:209], v[26:29]
	v_mfma_f32_16x16x32_bf16 v[22:25], v[174:177], v[206:209], v[22:25]
	v_mfma_f32_16x16x32_bf16 v[10:13], v[166:169], v[214:217], v[10:13]
	v_mfma_f32_16x16x32_bf16 v[6:9], v[174:177], v[214:217], v[6:9]
	v_mfma_f32_16x16x32_bf16 v[58:61], v[170:173], v[186:189], v[58:61]
	v_mfma_f32_16x16x32_bf16 v[54:57], v[178:181], v[186:189], v[54:57]
	v_mfma_f32_16x16x32_bf16 v[42:45], v[170:173], v[202:205], v[42:45]
	v_mfma_f32_16x16x32_bf16 v[38:41], v[178:181], v[202:205], v[38:41]
	v_mfma_f32_16x16x32_bf16 v[26:29], v[170:173], v[210:213], v[26:29]
	v_mfma_f32_16x16x32_bf16 v[22:25], v[178:181], v[210:213], v[22:25]
	v_mfma_f32_16x16x32_bf16 v[10:13], v[170:173], v[236:239], v[10:13]
	v_mfma_f32_16x16x32_bf16 v[6:9], v[178:181], v[236:239], v[6:9]
	s_setprio 0
	s_barrier
	s_add_i32 s64, 0, 0x18000
	s_add_i32 s65, 0, 0x1c000
	v_add_u32_e32 v156, s64, v163
	v_add_u32_e32 v178, s65, v163
	ds_read_b128 v[134:137], v156
	ds_read_b128 v[138:141], v156 offset:1024
	ds_read_b128 v[152:155], v156 offset:2048
	ds_read_b128 v[156:159], v156 offset:3072
	ds_read_b128 v[166:169], v178
	ds_read_b128 v[170:173], v178 offset:1024
	ds_read_b128 v[174:177], v178 offset:2048
	ds_read_b128 v[178:181], v178 offset:3072
	s_add_u32 s56, s56, 0x200000
	s_addc_u32 s57, s57, 0
	s_mov_b32 m0, s26
	v_lshl_add_u64 v[244:245], s[56:57], 0, v[142:143]
	ds_read_b128 v[182:185], v165 offset:32768
	ds_read_b128 v[186:189], v165 offset:33792
	ds_read_b128 v[198:201], v165 offset:34816
	ds_read_b128 v[202:205], v165 offset:35840
	ds_read_b128 v[206:209], v165 offset:36864
	ds_read_b128 v[210:213], v165 offset:37888
	ds_read_b128 v[214:217], v165 offset:38912
	ds_read_b128 v[236:239], v165 offset:39936
	global_load_lds_dwordx4 v[244:245], off
	v_lshl_add_u64 v[244:245], s[56:57], 0, v[144:145]
	s_mov_b32 m0, s29
	s_nop 0
	global_load_lds_dwordx4 v[244:245], off
	s_waitcnt vmcnt(8)
	s_waitcnt lgkmcnt(0)
	s_barrier
	s_setprio 1
	s_waitcnt lgkmcnt(0)
	v_mfma_f32_16x16x32_bf16 v[130:133], v[134:137], v[182:185], v[130:133]
	v_mfma_f32_16x16x32_bf16 v[126:129], v[152:155], v[182:185], v[126:129]
	v_mfma_f32_16x16x32_bf16 v[114:117], v[134:137], v[198:201], v[114:117]
	v_mfma_f32_16x16x32_bf16 v[110:113], v[152:155], v[198:201], v[110:113]
	v_mfma_f32_16x16x32_bf16 v[98:101], v[134:137], v[206:209], v[98:101]
	v_mfma_f32_16x16x32_bf16 v[94:97], v[152:155], v[206:209], v[94:97]
	v_mfma_f32_16x16x32_bf16 v[82:85], v[134:137], v[214:217], v[82:85]
	v_mfma_f32_16x16x32_bf16 v[78:81], v[152:155], v[214:217], v[78:81]
	v_mfma_f32_16x16x32_bf16 v[130:133], v[138:141], v[186:189], v[130:133]
	v_mfma_f32_16x16x32_bf16 v[126:129], v[156:159], v[186:189], v[126:129]
	v_mfma_f32_16x16x32_bf16 v[114:117], v[138:141], v[202:205], v[114:117]
	v_mfma_f32_16x16x32_bf16 v[110:113], v[156:159], v[202:205], v[110:113]
	v_mfma_f32_16x16x32_bf16 v[98:101], v[138:141], v[210:213], v[98:101]
	v_mfma_f32_16x16x32_bf16 v[94:97], v[156:159], v[210:213], v[94:97]
	v_mfma_f32_16x16x32_bf16 v[82:85], v[138:141], v[236:239], v[82:85]
	v_mfma_f32_16x16x32_bf16 v[78:81], v[156:159], v[236:239], v[78:81]
	s_setprio 0
	s_setprio 1
	v_mfma_f32_16x16x32_bf16 v[122:125], v[166:169], v[182:185], v[122:125]
	v_mfma_f32_16x16x32_bf16 v[118:121], v[174:177], v[182:185], v[118:121]
	v_mfma_f32_16x16x32_bf16 v[106:109], v[166:169], v[198:201], v[106:109]
	v_mfma_f32_16x16x32_bf16 v[102:105], v[174:177], v[198:201], v[102:105]
	v_mfma_f32_16x16x32_bf16 v[90:93], v[166:169], v[206:209], v[90:93]
	v_mfma_f32_16x16x32_bf16 v[86:89], v[174:177], v[206:209], v[86:89]
	v_mfma_f32_16x16x32_bf16 v[74:77], v[166:169], v[214:217], v[74:77]
	v_mfma_f32_16x16x32_bf16 v[70:73], v[174:177], v[214:217], v[70:73]
	v_mfma_f32_16x16x32_bf16 v[122:125], v[170:173], v[186:189], v[122:125]
	v_mfma_f32_16x16x32_bf16 v[118:121], v[178:181], v[186:189], v[118:121]
	v_mfma_f32_16x16x32_bf16 v[106:109], v[170:173], v[202:205], v[106:109]
	v_mfma_f32_16x16x32_bf16 v[102:105], v[178:181], v[202:205], v[102:105]
	v_mfma_f32_16x16x32_bf16 v[90:93], v[170:173], v[210:213], v[90:93]
	v_mfma_f32_16x16x32_bf16 v[86:89], v[178:181], v[210:213], v[86:89]
	v_mfma_f32_16x16x32_bf16 v[74:77], v[170:173], v[236:239], v[74:77]
	v_mfma_f32_16x16x32_bf16 v[70:73], v[178:181], v[236:239], v[70:73]
	s_setprio 0
	s_barrier
	s_add_i32 s56, s64, s15
	v_lshl_add_u64 v[160:161], v[160:161], 0, s[30:31]
	s_mov_b32 m0, s56
	ds_read_b128 v[182:185], v165 offset:49152
	ds_read_b128 v[186:189], v165 offset:50176
	ds_read_b128 v[198:201], v165 offset:51200
	ds_read_b128 v[202:205], v165 offset:52224
	ds_read_b128 v[206:209], v165 offset:53248
	ds_read_b128 v[210:213], v165 offset:54272
	ds_read_b128 v[214:217], v165 offset:55296
	ds_read_b128 v[236:239], v165 offset:56320
	global_load_lds_dwordx4 v[160:161], off
	s_add_i32 m0, s56, 0x2000
	s_add_u32 s54, s54, 0x200080
	v_lshl_add_u64 v[160:161], v[218:219], 0, s[30:31]
	s_addc_u32 s55, s55, 0
	s_add_i32 s56, s65, s15
	global_load_lds_dwordx4 v[160:161], off
	v_lshl_add_u64 v[160:161], s[54:55], 0, v[190:191]
	s_mov_b32 m0, s56
	s_nop 0
	global_load_lds_dwordx4 v[160:161], off
	v_lshl_add_u64 v[160:161], s[54:55], 0, v[146:147]
	s_add_i32 m0, s56, 0x2000
	s_nop 0
	global_load_lds_dwordx4 v[160:161], off
	v_lshl_add_u64 v[160:161], v[240:241], 0, s[30:31]
	s_mov_b32 m0, s51
	s_nop 0
	global_load_lds_dwordx4 v[160:161], off
	v_lshl_add_u64 v[160:161], v[242:243], 0, s[30:31]
	s_mov_b32 m0, s58
	s_nop 0
	global_load_lds_dwordx4 v[160:161], off
	s_waitcnt vmcnt(8)
	s_waitcnt lgkmcnt(0)
	s_barrier
	s_setprio 1
	s_waitcnt lgkmcnt(0)
	v_mfma_f32_16x16x32_bf16 v[66:69], v[134:137], v[182:185], v[66:69]
	v_mfma_f32_16x16x32_bf16 v[62:65], v[152:155], v[182:185], v[62:65]
	v_mfma_f32_16x16x32_bf16 v[50:53], v[134:137], v[198:201], v[50:53]
	v_mfma_f32_16x16x32_bf16 v[46:49], v[152:155], v[198:201], v[46:49]
	v_mfma_f32_16x16x32_bf16 v[34:37], v[134:137], v[206:209], v[34:37]
	v_mfma_f32_16x16x32_bf16 v[30:33], v[152:155], v[206:209], v[30:33]
	v_mfma_f32_16x16x32_bf16 v[18:21], v[134:137], v[214:217], v[18:21]
	v_mfma_f32_16x16x32_bf16 v[14:17], v[152:155], v[214:217], v[14:17]
	v_mfma_f32_16x16x32_bf16 v[66:69], v[138:141], v[186:189], v[66:69]
	v_mfma_f32_16x16x32_bf16 v[62:65], v[156:159], v[186:189], v[62:65]
	v_mfma_f32_16x16x32_bf16 v[50:53], v[138:141], v[202:205], v[50:53]
	v_mfma_f32_16x16x32_bf16 v[46:49], v[156:159], v[202:205], v[46:49]
	v_mfma_f32_16x16x32_bf16 v[34:37], v[138:141], v[210:213], v[34:37]
	v_mfma_f32_16x16x32_bf16 v[30:33], v[156:159], v[210:213], v[30:33]
	v_mfma_f32_16x16x32_bf16 v[18:21], v[138:141], v[236:239], v[18:21]
	v_mfma_f32_16x16x32_bf16 v[14:17], v[156:159], v[236:239], v[14:17]
	s_setprio 0
	s_setprio 1
	v_mfma_f32_16x16x32_bf16 v[58:61], v[166:169], v[182:185], v[58:61]
	v_mfma_f32_16x16x32_bf16 v[54:57], v[174:177], v[182:185], v[54:57]
	v_mfma_f32_16x16x32_bf16 v[42:45], v[166:169], v[198:201], v[42:45]
	v_mfma_f32_16x16x32_bf16 v[38:41], v[174:177], v[198:201], v[38:41]
	v_mfma_f32_16x16x32_bf16 v[26:29], v[166:169], v[206:209], v[26:29]
	v_mfma_f32_16x16x32_bf16 v[22:25], v[174:177], v[206:209], v[22:25]
	v_mfma_f32_16x16x32_bf16 v[10:13], v[166:169], v[214:217], v[10:13]
	v_mfma_f32_16x16x32_bf16 v[6:9], v[174:177], v[214:217], v[6:9]
	v_mfma_f32_16x16x32_bf16 v[58:61], v[170:173], v[186:189], v[58:61]
	v_mfma_f32_16x16x32_bf16 v[54:57], v[178:181], v[186:189], v[54:57]
	v_mfma_f32_16x16x32_bf16 v[42:45], v[170:173], v[202:205], v[42:45]
	v_mfma_f32_16x16x32_bf16 v[38:41], v[178:181], v[202:205], v[38:41]
	v_mfma_f32_16x16x32_bf16 v[26:29], v[170:173], v[210:213], v[26:29]
	v_mfma_f32_16x16x32_bf16 v[22:25], v[178:181], v[210:213], v[22:25]
	v_mfma_f32_16x16x32_bf16 v[10:13], v[170:173], v[236:239], v[10:13]
	v_mfma_f32_16x16x32_bf16 v[6:9], v[178:181], v[236:239], v[6:9]
	s_setprio 0
	s_barrier
	s_add_i32 s63, s63, 2
	s_add_u32 s61, s61, 0x100
	s_addc_u32 s62, s62, 0
	s_add_u32 s52, s52, 0x100
	s_addc_u32 s53, s53, 0
	s_cmpk_gt_u32 s63, 0x7d
	s_cbranch_scc0 .LBB0_41
	s_cmp_lg_u32 s94, 8
	s_cbranch_scc1 .Lwarm_in_skip
	v_lshl_add_u32 v246, s80, 9, v235
	v_lshlrev_b32_e32 v246, 7, v246
	v_add_u32_e32 v248, 0xe80000, v246
	v_add_u32_e32 v246, 0x100000, v246
	v_mov_b32_e32 v247, 0
	v_mov_b32_e32 v249, 0
	v_lshl_add_u64 v[246:247], s[12:13], 0, v[246:247]
	v_lshl_add_u64 v[248:249], s[12:13], 0, v[248:249]
	global_load_dword v250, v[246:247], off
	global_load_dword v250, v[248:249], off
.Lwarm_in_skip:
	v_lshl_or_b32 v152, s50, 8, v164
	v_lshl_add_u32 v154, s48, 8, v162
	v_ashrrev_i32_e32 v153, 31, v152
	v_readlane_b32 s4, v255, 14
	v_ashrrev_i32_e32 v155, 31, v154
	v_lshlrev_b64 v[176:177], 1, v[152:153]
	v_readlane_b32 s5, v255, 15
	v_lshlrev_b64 v[158:159], 12, v[154:155]
	v_or_b32_e32 v160, 16, v154
	v_lshl_add_u64 v[156:157], s[4:5], 0, v[176:177]
	v_lshl_add_u64 v[134:135], v[156:157], 0, v[158:159]
	global_load_dwordx4 v[168:171], v[134:135], off
	global_load_dwordx4 v[172:175], v[134:135], off offset:256
	v_ashrrev_i32_e32 v161, 31, v160
	v_lshlrev_b64 v[134:135], 12, v[160:161]
	v_lshl_add_u64 v[134:135], v[156:157], 0, v[134:135]
	global_load_dwordx4 v[138:141], v[134:135], off
	s_nop 0
	global_load_dwordx4 v[134:137], v[134:135], off offset:256
	v_and_b32_e32 v167, 64, v221
	v_xor_b32_e32 v166, 16, v221
	v_add_u32_e32 v167, 64, v167
	v_xor_b32_e32 v178, 32, v221
	v_cmp_lt_i32_e32 vcc, v166, v167
	s_waitcnt vmcnt(0)
	v_lshlrev_b32_e32 v180, 16, v170
	v_cndmask_b32_e32 v166, v221, v166, vcc
	v_cmp_lt_i32_e32 vcc, v178, v167
	v_and_b32_e32 v181, 0xffff0000, v170
	v_lshlrev_b32_e32 v170, 16, v171
	v_cndmask_b32_e32 v167, v221, v178, vcc
	v_lshl_add_u64 v[178:179], s[4:5], 0, v[158:159]
	v_lshl_add_u64 v[176:177], v[178:179], 0, v[176:177]
	v_lshlrev_b32_e32 v178, 16, v168
	v_and_b32_e32 v179, 0xffff0000, v168
	v_lshlrev_b32_e32 v168, 16, v169
	v_and_b32_e32 v169, 0xffff0000, v169
	v_and_b32_e32 v171, 0xffff0000, v171
	v_lshlrev_b32_e32 v182, 16, v172
	v_and_b32_e32 v183, 0xffff0000, v172
	v_lshlrev_b32_e32 v172, 16, v173
	v_and_b32_e32 v173, 0xffff0000, v173
	v_lshlrev_b32_e32 v184, 16, v174
	v_and_b32_e32 v185, 0xffff0000, v174
	v_lshlrev_b32_e32 v174, 16, v175
	v_and_b32_e32 v175, 0xffff0000, v175
	v_pk_add_f32 v[132:133], v[132:133], v[168:169]
	v_pk_add_f32 v[130:131], v[130:131], v[178:179]
	v_pk_add_f32 v[128:129], v[128:129], v[170:171]
	v_pk_add_f32 v[126:127], v[126:127], v[180:181]
	v_pk_add_f32 v[168:169], v[124:125], v[172:173]
	v_pk_add_f32 v[122:123], v[122:123], v[182:183]
	v_pk_add_f32 v[170:171], v[120:121], v[174:175]
	v_pk_add_f32 v[172:173], v[118:119], v[184:185]
	v_mul_f32_e32 v121, v131, v131
	v_mul_f32_e32 v124, v133, v133
	v_mul_f32_e32 v125, v127, v127
	v_mul_f32_e32 v174, v129, v129
	v_cvt_pk_bf16_f32 v118, v130, v131
	v_cvt_pk_bf16_f32 v119, v132, v133
	v_cvt_pk_bf16_f32 v120, v126, v127
	v_mul_f32_e32 v127, v123, v123
	v_mul_f32_e32 v131, v169, v169
	v_mul_f32_e32 v133, v173, v173
	v_mul_f32_e32 v175, v171, v171
	v_fmac_f32_e32 v121, v130, v130
	v_fmac_f32_e32 v124, v132, v132
	v_fmac_f32_e32 v125, v126, v126
	v_fmac_f32_e32 v174, v128, v128
	v_fmac_f32_e32 v127, v122, v122
	v_fmac_f32_e32 v131, v168, v168
	v_fmac_f32_e32 v133, v172, v172
	v_fmac_f32_e32 v175, v170, v170
	v_add_f32_e32 v121, v121, v124
	v_add_f32_e32 v124, v125, v174
	v_add_f32_e32 v125, v127, v131
	v_add_f32_e32 v126, v133, v175
	v_add_f32_e32 v121, v121, v124
	v_add_f32_e32 v124, v125, v126
	v_lshlrev_b32_e32 v166, 2, v166
	v_add_f32_e32 v126, v121, v124
	ds_bpermute_b32 v127, v166, v126
	v_cvt_pk_bf16_f32 v121, v128, v129
	global_store_dwordx4 v[176:177], v[118:121], off
	v_cvt_pk_bf16_f32 v124, v122, v123
	v_cvt_pk_bf16_f32 v125, v168, v169
	s_waitcnt lgkmcnt(0)
	s_nop 0
	v_add_f32_e32 v121, v126, v127
	v_lshlrev_b32_e32 v120, 2, v167
	ds_bpermute_b32 v122, v120, v121
	v_lshl_add_u64 v[118:119], v[154:155], 3, s[18:19]
	v_cvt_pk_bf16_f32 v126, v172, v173
	v_cvt_pk_bf16_f32 v127, v170, v171
	global_store_dwordx4 v[176:177], v[124:127], off offset:256
	s_and_saveexec_b64 s[4:5], s[38:39]
	s_cbranch_execz .LBB0_44
	s_waitcnt lgkmcnt(0)
	v_add_f32_e32 v121, v121, v122
	v_mul_f32_e32 v121, 0x4b800000, v121
	v_trunc_f32_e32 v121, v121
	v_mul_f32_e32 v122, 0x2f800000, v121
	v_floor_f32_e32 v123, v122
	v_fmac_f32_e32 v121, 0xcf800000, v123
	v_cvt_u32_f32_e32 v122, v121
	v_cvt_u32_f32_e32 v123, v123
	global_atomic_add_x2 v[118:119], v[122:123], off

.LBB0_73:
	s_add_i32 s60, s60, 1
	s_cmp_lg_u32 s60, 4
	s_cbranch_scc1 .Lwarm_dn_skip
	v_lshl_add_u32 v246, s80, 9, v235
	v_lshlrev_b32_e32 v246, 7, v246
	v_add_u32_e32 v248, 0x5400000, v246
	v_add_u32_e32 v246, 0x4400000, v246
	v_mov_b32_e32 v247, 0
	v_mov_b32_e32 v249, 0
	v_lshl_add_u64 v[246:247], s[12:13], 0, v[246:247]
	v_lshl_add_u64 v[248:249], s[12:13], 0, v[248:249]
	global_load_dword v250, v[246:247], off
	global_load_dword v250, v[248:249], off
.Lwarm_dn_skip:
	s_mul_i32 s4, s60, s53
	s_mul_hi_u32 s5, s60, s22
	s_add_i32 s5, s5, s4
	s_mul_i32 s4, s60, s22
	s_add_u32 s4, s4, s80
	s_addc_u32 s5, s5, s0
	v_mov_b64_e32 v[6:7], 0x400
	v_cmp_lt_i64_e64 s[38:39], s[4:5], v[6:7]
	v_mov_b64_e32 v[6:7], 0x3ff
	v_cmp_gt_i64_e32 vcc, s[4:5], v[6:7]
	s_cbranch_vccnz .LBB0_79
	s_ashr_i32 s5, s4, 31
	s_lshr_b32 s5, s5, 29
	s_add_i32 s44, s4, s5
	s_and_b32 s5, s44, -8
	s_sub_i32 s45, s4, s5
	s_cmp_gt_i32 s45, -1
	s_mov_b64 s[4:5], -1
	s_cbranch_scc0 .LBB0_76
	s_lshl_b32 s46, s45, 7
	s_mov_b64 s[4:5], 0
